# RG-LRU pass 2: carry staging loads issued together (17 in flight) instead of 17 serialized load-wait-write trips per direction
# speedup vs baseline: 1.0180x; 1.0130x over previous
; template <int PASS>
; __device__ __forceinline__ void rglru_phase(const Ctx& F, int l, const bf16_t* XRb, bf16_t* GRb, bool latent_only = false) {
;     ...
;                 __builtin_amdgcn_wave_barrier();
;                 for (int k = l4; k < NCH; k += 4) AB[k * 16 + l15] = AGG[((size_t)(b * 2 + d) * NCH + k) * 1024 + ch];
;                 asm volatile("s_waitcnt vmcnt(0) lgkmcnt(0)" ::: "memory"); __builtin_amdgcn_wave_barrier();
.LBB0_486:
	s_mov_b64 s[62:63], 0x8000
	global_load_dwordx2 v[106:107], v[68:69], off
	v_lshl_add_u64 v[68:69], v[68:69], 0, s[62:63]
	global_load_dwordx2 v[108:109], v[68:69], off
	v_lshl_add_u64 v[68:69], v[68:69], 0, s[62:63]
	global_load_dwordx2 v[110:111], v[68:69], off
	v_lshl_add_u64 v[68:69], v[68:69], 0, s[62:63]
	global_load_dwordx2 v[112:113], v[68:69], off
	v_lshl_add_u64 v[68:69], v[68:69], 0, s[62:63]
	global_load_dwordx2 v[114:115], v[68:69], off
	v_lshl_add_u64 v[68:69], v[68:69], 0, s[62:63]
	global_load_dwordx2 v[116:117], v[68:69], off
	v_lshl_add_u64 v[68:69], v[68:69], 0, s[62:63]
	global_load_dwordx2 v[118:119], v[68:69], off
	v_lshl_add_u64 v[68:69], v[68:69], 0, s[62:63]
	global_load_dwordx2 v[120:121], v[68:69], off
	v_lshl_add_u64 v[68:69], v[68:69], 0, s[62:63]
	global_load_dwordx2 v[122:123], v[68:69], off
	v_lshl_add_u64 v[68:69], v[68:69], 0, s[62:63]
	global_load_dwordx2 v[124:125], v[68:69], off
	v_lshl_add_u64 v[68:69], v[68:69], 0, s[62:63]
	global_load_dwordx2 v[126:127], v[68:69], off
	v_lshl_add_u64 v[68:69], v[68:69], 0, s[62:63]
	global_load_dwordx2 v[128:129], v[68:69], off
	v_lshl_add_u64 v[68:69], v[68:69], 0, s[62:63]
	global_load_dwordx2 v[130:131], v[68:69], off
	v_lshl_add_u64 v[68:69], v[68:69], 0, s[62:63]
	global_load_dwordx2 v[132:133], v[68:69], off
	v_lshl_add_u64 v[68:69], v[68:69], 0, s[62:63]
	global_load_dwordx2 v[134:135], v[68:69], off
	v_lshl_add_u64 v[68:69], v[68:69], 0, s[62:63]
	global_load_dwordx2 v[136:137], v[68:69], off
	v_lshl_add_u64 v[68:69], v[68:69], 0, s[62:63]
	global_load_dwordx2 v[138:139], v[68:69], off
	s_waitcnt vmcnt(0)
	ds_write_b64 v32, v[106:107]
	ds_write_b64 v32, v[108:109] offset:512
	ds_write_b64 v32, v[110:111] offset:1024
	ds_write_b64 v32, v[112:113] offset:1536
	ds_write_b64 v32, v[114:115] offset:2048
	ds_write_b64 v32, v[116:117] offset:2560
	ds_write_b64 v32, v[118:119] offset:3072
	ds_write_b64 v32, v[120:121] offset:3584
	ds_write_b64 v32, v[122:123] offset:4096
	ds_write_b64 v32, v[124:125] offset:4608
	ds_write_b64 v32, v[126:127] offset:5120
	ds_write_b64 v32, v[128:129] offset:5632
	ds_write_b64 v32, v[130:131] offset:6144
	ds_write_b64 v32, v[132:133] offset:6656
	ds_write_b64 v32, v[134:135] offset:7168
	ds_write_b64 v32, v[136:137] offset:7680
	ds_write_b64 v32, v[138:139] offset:8192
